# sample-attn staging conversion: nine LDS reads up front with counted lgkmcnt, in-place cvt
# baseline (speedup 1.0000x reference)
.LBB0_1875:
	s_waitcnt vmcnt(0)
	s_barrier
	ds_read_b128 v[150:153], v169
	ds_read_b128 v[154:157], v169 offset:8192
	ds_read_b128 v[196:199], v169 offset:16384
	ds_read_b128 v[200:203], v169 offset:24576
	ds_read_b128 v[214:217], v169 offset:32768
	ds_read_b128 v[218:221], v169 offset:40960
	ds_read_b128 v[222:225], v169 offset:49152
	ds_read_b128 v[238:241], v169 offset:57344
	ds_read_b128 v[242:245], v181
	s_waitcnt lgkmcnt(8)
	v_cvt_pk_bf16_f32 v150, v150, v151
	v_cvt_pk_bf16_f32 v151, v152, v153
	ds_write_b64 v171, v[150:151]
	s_waitcnt lgkmcnt(8)
	v_cvt_pk_bf16_f32 v154, v154, v155
	v_cvt_pk_bf16_f32 v155, v156, v157
	ds_write_b64 v171, v[154:155] offset:4224
	s_waitcnt lgkmcnt(8)
	v_cvt_pk_bf16_f32 v196, v196, v197
	v_cvt_pk_bf16_f32 v197, v198, v199
	ds_write_b64 v171, v[196:197] offset:8448
	s_waitcnt lgkmcnt(8)
	v_cvt_pk_bf16_f32 v200, v200, v201
	v_cvt_pk_bf16_f32 v201, v202, v203
	ds_write_b64 v171, v[200:201] offset:12672
	s_waitcnt lgkmcnt(8)
	v_cvt_pk_bf16_f32 v214, v214, v215
	v_cvt_pk_bf16_f32 v215, v216, v217
	ds_write_b64 v171, v[214:215] offset:16896
	s_waitcnt lgkmcnt(8)
	v_cvt_pk_bf16_f32 v218, v218, v219
	v_cvt_pk_bf16_f32 v219, v220, v221
	ds_write_b64 v171, v[218:219] offset:21120
	s_waitcnt lgkmcnt(8)
	v_cvt_pk_bf16_f32 v222, v222, v223
	v_cvt_pk_bf16_f32 v223, v224, v225
	ds_write_b64 v171, v[222:223] offset:25344
	s_waitcnt lgkmcnt(8)
	v_cvt_pk_bf16_f32 v238, v238, v239
	v_cvt_pk_bf16_f32 v239, v240, v241
	ds_write_b64 v171, v[238:239] offset:29568
	s_waitcnt lgkmcnt(8)
	v_cvt_pk_bf16_f32 v150, v242, v243
	v_cvt_pk_bf16_f32 v151, v244, v245
	ds_write_b64 v182, v[150:151]
	v_and_b32_e32 v149, 0xffff0000, v150
	v_lshlrev_b32_e32 v147, 16, v150
	v_mul_f32_e32 v149, v149, v149
	v_fmac_f32_e32 v149, v147, v147
	v_and_b32_e32 v147, 0xffff0000, v151
	v_lshlrev_b32_e32 v150, 16, v151
	v_mul_f32_e32 v147, v147, v147
	v_fmac_f32_e32 v147, v150, v150
	v_add_f32_e32 v147, v149, v147
	s_nop 1
	v_add_f32_dpp v147, v147, v147 quad_perm:[1,0,3,2] row_mask:0xf bank_mask:0xf bound_ctrl:1
	s_nop 1
	v_add_f32_dpp v147, v147, v147 quad_perm:[2,3,0,1] row_mask:0xf bank_mask:0xf bound_ctrl:1
	s_nop 1
	v_mov_b32_dpp v149, v147 row_half_mirror row_mask:0xf bank_mask:0xf bound_ctrl:1
	s_and_saveexec_b64 s[50:51], s[2:3]
	v_add_f32_e32 v147, v147, v149
	ds_write_b32 v189, v147
	s_or_b64 exec, exec, s[50:51]
	s_add_i32 s78, s78, 1
	s_cmp_ge_i32 s78, s62
	s_cselect_b64 s[50:51], -1, 0
	s_or_b64 s[48:49], s[48:49], s[50:51]
	s_nor_b64 s[50:51], s[0:1], s[48:49]
	s_and_saveexec_b64 s[48:49], s[50:51]
	s_cbranch_execz .LBB0_1862
	s_add_i32 s47, s81, 1
	s_mul_i32 s50, s47, s24
	s_add_i32 s50, s50, s25
	s_ashr_i32 s50, s50, 3
	s_and_b32 s50, s50, -4
	v_add_u32_e32 v147, s50, v190
	v_ashrrev_i32_e32 v149, 31, v147
	v_lshl_or_b32 v147, v147, 3, v170
	v_mad_u64_u32 v[150:151], s[50:51], v147, s33, v[172:173]
	v_mad_i32_i24 v151, v149, s33, v151
	global_load_dwordx4 v[150:153], v[150:151], off
	s_bitcmp1_b32 s47, 0
	s_cselect_b32 s47, 0x1800, 0
	v_add_u32_e32 v147, s47, v191
	s_waitcnt vmcnt(0)
	ds_write_b128 v147, v[150:153]
	s_branch .LBB0_1862
